# v6_rot
# speedup vs baseline: 1.2742x; 1.0071x over previous
.LBB0_73:
	s_cmp_eq_u32 s15, 0x30400
	s_mov_b32 s2, 0x10000
	s_and_b32 s2, s13, 0x10000
	s_xor_b32 s10, s2, 0x10000
	s_add_i32 s16, s21, s10
	s_add_i32 s17, s15, 0xfffd0000
	s_add_i32 s30, s16, 0x8000
	s_mov_b32 s10, s66
	s_mov_b32 s11, s67
	s_waitcnt lgkmcnt(0)
	v_add_u32_e32 v228, s2, v138
	v_add_u32_e32 v229, s2, v136
	ds_read_b128 v[132:135], v229 offset:0
	ds_read_b128 v[140:143], v229 offset:0x800
	ds_read_b128 v[144:147], v229 offset:0x1000
	ds_read_b128 v[148:151], v229 offset:0x1800
	ds_read_b128 v[152:155], v228 offset:0
	ds_read_b128 v[156:159], v228 offset:0x800
	s_setprio 1
	s_mov_b32 m0, s16
	s_nop 0
	buffer_load_dwordx4 v131, s[64:67], s17 offen lds
	s_mov_b32 m0, s30
	s_nop 0
	buffer_load_dwordx4 v131, s[8:11], s17 offen lds
	s_add_i32 m0, s16, 0x2000
	s_add_i32 s17, s15, 0xfffe0000
	buffer_load_dwordx4 v131, s[64:67], s17 offen lds
	s_add_i32 m0, s16, 0xa000
	s_nop 0
	buffer_load_dwordx4 v131, s[8:11], s17 offen lds
	ds_read_b128 v[160:163], v228 offset:0x1000
	v_xor_b32_e32 v176, 64, v228
	s_branch .Lrot3_mid_l
.Lrot3_top_l:
	s_and_b32 s2, s13, 0x10000
	s_xor_b32 s10, s2, 0x10000
	s_add_i32 s16, s21, s10
	s_add_i32 s17, s15, 0xfffd0000
	s_add_i32 s30, s16, 0x8000
	s_mov_b32 s10, s66
	s_mov_b32 s11, s67
	v_add_u32_e32 v228, s2, v138
	v_add_u32_e32 v229, s2, v136
	ds_read_b128 v[132:135], v229 offset:0
	ds_read_b128 v[140:143], v229 offset:0x800
	ds_read_b128 v[144:147], v229 offset:0x1000
	ds_read_b128 v[148:151], v229 offset:0x1800
	ds_read_b128 v[152:155], v228 offset:0
	ds_read_b128 v[156:159], v228 offset:0x800
	s_setprio 1
	s_mov_b32 m0, s16
	s_nop 0
	buffer_load_dwordx4 v131, s[64:67], s17 offen lds
	s_mov_b32 m0, s30
	s_nop 0
	buffer_load_dwordx4 v131, s[8:11], s17 offen lds
	v_mfma_f32_16x16x32_bf16 v[46:49], v[236:239], v[160:163], v[46:49]
	v_mfma_f32_16x16x32_bf16 v[42:45], v[236:239], v[164:167], v[42:45]
	v_mfma_f32_16x16x32_bf16 v[38:41], v[236:239], v[168:171], v[38:41]
	v_mfma_f32_16x16x32_bf16 v[34:37], v[236:239], v[232:235], v[34:37]
	s_add_i32 m0, s16, 0x2000
	s_add_i32 s17, s15, 0xfffe0000
	buffer_load_dwordx4 v131, s[64:67], s17 offen lds
	v_mfma_f32_16x16x32_bf16 v[30:33], v[240:243], v[160:163], v[30:33]
	v_mfma_f32_16x16x32_bf16 v[26:29], v[240:243], v[164:167], v[26:29]
	v_mfma_f32_16x16x32_bf16 v[22:25], v[240:243], v[168:171], v[22:25]
	v_mfma_f32_16x16x32_bf16 v[18:21], v[240:243], v[232:235], v[18:21]
	s_add_i32 m0, s16, 0xa000
	s_nop 0
	buffer_load_dwordx4 v131, s[8:11], s17 offen lds
	v_mfma_f32_16x16x32_bf16 v[14:17], v[244:247], v[160:163], v[14:17]
	v_mfma_f32_16x16x32_bf16 v[10:13], v[244:247], v[164:167], v[10:13]
	v_mfma_f32_16x16x32_bf16 v[6:9], v[244:247], v[168:171], v[6:9]
	v_mfma_f32_16x16x32_bf16 v[2:5], v[244:247], v[232:235], v[2:5]
	ds_read_b128 v[160:163], v228 offset:0x1000
	v_xor_b32_e32 v176, 64, v228
.Lrot3_mid_l:
	s_waitcnt lgkmcnt(2)
	s_nop 0
	v_mfma_f32_16x16x32_bf16 v[126:129], v[152:155], v[132:135], v[126:129]
	v_mfma_f32_16x16x32_bf16 v[122:125], v[152:155], v[140:143], v[122:125]
	v_mfma_f32_16x16x32_bf16 v[118:121], v[152:155], v[144:147], v[118:121]
	v_mfma_f32_16x16x32_bf16 v[114:117], v[152:155], v[148:151], v[114:117]
	s_add_i32 m0, s16, 0x4000
	s_add_i32 s17, s15, 0xffff0000
	buffer_load_dwordx4 v131, s[64:67], s17 offen lds
	ds_read_b128 v[152:155], v228 offset:0x1800
	s_waitcnt lgkmcnt(2)
	s_nop 0
	v_mfma_f32_16x16x32_bf16 v[110:113], v[156:159], v[132:135], v[110:113]
	v_mfma_f32_16x16x32_bf16 v[106:109], v[156:159], v[140:143], v[106:109]
	v_mfma_f32_16x16x32_bf16 v[102:105], v[156:159], v[144:147], v[102:105]
	v_mfma_f32_16x16x32_bf16 v[98:101], v[156:159], v[148:151], v[98:101]
	s_add_i32 m0, s16, 0xc000
	s_nop 0
	buffer_load_dwordx4 v131, s[8:11], s17 offen lds
	ds_read_b128 v[156:159], v228 offset:0x2000
	s_waitcnt lgkmcnt(2)
	s_nop 0
	v_mfma_f32_16x16x32_bf16 v[94:97], v[160:163], v[132:135], v[94:97]
	v_mfma_f32_16x16x32_bf16 v[90:93], v[160:163], v[140:143], v[90:93]
	v_mfma_f32_16x16x32_bf16 v[86:89], v[160:163], v[144:147], v[86:89]
	v_mfma_f32_16x16x32_bf16 v[82:85], v[160:163], v[148:151], v[82:85]
	s_add_i32 m0, s16, 0x6000
	s_nop 0
	buffer_load_dwordx4 v131, s[64:67], s15 offen lds
	ds_read_b128 v[160:163], v228 offset:0x2800
	s_waitcnt lgkmcnt(2)
	s_nop 0
	v_mfma_f32_16x16x32_bf16 v[78:81], v[152:155], v[132:135], v[78:81]
	v_mfma_f32_16x16x32_bf16 v[74:77], v[152:155], v[140:143], v[74:77]
	v_mfma_f32_16x16x32_bf16 v[70:73], v[152:155], v[144:147], v[70:73]
	v_mfma_f32_16x16x32_bf16 v[66:69], v[152:155], v[148:151], v[66:69]
	s_add_i32 m0, s16, 0xe000
	s_nop 0
	buffer_load_dwordx4 v131, s[8:11], s15 offen lds
	ds_read_b128 v[152:155], v228 offset:0x3000
	s_waitcnt lgkmcnt(2)
	s_nop 0
	v_mfma_f32_16x16x32_bf16 v[62:65], v[156:159], v[132:135], v[62:65]
	v_mfma_f32_16x16x32_bf16 v[58:61], v[156:159], v[140:143], v[58:61]
	v_mfma_f32_16x16x32_bf16 v[54:57], v[156:159], v[144:147], v[54:57]
	v_mfma_f32_16x16x32_bf16 v[50:53], v[156:159], v[148:151], v[50:53]
	ds_read_b128 v[156:159], v228 offset:0x3800
	s_waitcnt lgkmcnt(2)
	v_xor_b32_e32 v0, 64, v229
	v_mfma_f32_16x16x32_bf16 v[46:49], v[160:163], v[132:135], v[46:49]
	v_mfma_f32_16x16x32_bf16 v[42:45], v[160:163], v[140:143], v[42:45]
	v_mfma_f32_16x16x32_bf16 v[38:41], v[160:163], v[144:147], v[38:41]
	v_mfma_f32_16x16x32_bf16 v[34:37], v[160:163], v[148:151], v[34:37]
	ds_read_b128 v[160:163], v0 offset:0
	ds_read_b128 v[164:167], v0 offset:0x800
	ds_read_b128 v[168:171], v0 offset:0x1000
	s_waitcnt lgkmcnt(4)
	s_nop 0
	v_mfma_f32_16x16x32_bf16 v[30:33], v[152:155], v[132:135], v[30:33]
	v_mfma_f32_16x16x32_bf16 v[26:29], v[152:155], v[140:143], v[26:29]
	v_mfma_f32_16x16x32_bf16 v[22:25], v[152:155], v[144:147], v[22:25]
	v_mfma_f32_16x16x32_bf16 v[18:21], v[152:155], v[148:151], v[18:21]
	ds_read_b128 v[232:235], v0 offset:0x1800
	ds_read_b128 v[172:175], v176 offset:0
	ds_read_b128 v[202:205], v176 offset:0x800
	s_waitcnt lgkmcnt(6)
	s_nop 0
	v_mfma_f32_16x16x32_bf16 v[14:17], v[156:159], v[132:135], v[14:17]
	v_mfma_f32_16x16x32_bf16 v[10:13], v[156:159], v[140:143], v[10:13]
	v_mfma_f32_16x16x32_bf16 v[6:9], v[156:159], v[144:147], v[6:9]
	v_mfma_f32_16x16x32_bf16 v[2:5], v[156:159], v[148:151], v[2:5]
	ds_read_b128 v[132:135], v176 offset:0x1000
	s_waitcnt lgkmcnt(2)
	s_nop 0
	v_mfma_f32_16x16x32_bf16 v[126:129], v[172:175], v[160:163], v[126:129]
	v_mfma_f32_16x16x32_bf16 v[122:125], v[172:175], v[164:167], v[122:125]
	v_mfma_f32_16x16x32_bf16 v[118:121], v[172:175], v[168:171], v[118:121]
	v_mfma_f32_16x16x32_bf16 v[114:117], v[172:175], v[232:235], v[114:117]
	ds_read_b128 v[140:143], v176 offset:0x1800
	s_waitcnt lgkmcnt(2)
	s_nop 0
	v_mfma_f32_16x16x32_bf16 v[110:113], v[202:205], v[160:163], v[110:113]
	v_mfma_f32_16x16x32_bf16 v[106:109], v[202:205], v[164:167], v[106:109]
	v_mfma_f32_16x16x32_bf16 v[102:105], v[202:205], v[168:171], v[102:105]
	v_mfma_f32_16x16x32_bf16 v[98:101], v[202:205], v[232:235], v[98:101]
	ds_read_b128 v[144:147], v176 offset:0x2000
	ds_read_b128 v[236:239], v176 offset:0x2800
	s_waitcnt lgkmcnt(3)
	s_nop 0
	v_mfma_f32_16x16x32_bf16 v[94:97], v[132:135], v[160:163], v[94:97]
	v_mfma_f32_16x16x32_bf16 v[90:93], v[132:135], v[164:167], v[90:93]
	v_mfma_f32_16x16x32_bf16 v[86:89], v[132:135], v[168:171], v[86:89]
	v_mfma_f32_16x16x32_bf16 v[82:85], v[132:135], v[232:235], v[82:85]
	ds_read_b128 v[240:243], v176 offset:0x3000
	s_waitcnt lgkmcnt(3)
	s_nop 0
	v_mfma_f32_16x16x32_bf16 v[78:81], v[140:143], v[160:163], v[78:81]
	v_mfma_f32_16x16x32_bf16 v[74:77], v[140:143], v[164:167], v[74:77]
	v_mfma_f32_16x16x32_bf16 v[70:73], v[140:143], v[168:171], v[70:73]
	v_mfma_f32_16x16x32_bf16 v[66:69], v[140:143], v[232:235], v[66:69]
	ds_read_b128 v[244:247], v176 offset:0x3800
	s_waitcnt lgkmcnt(3)
	s_nop 0
	v_mfma_f32_16x16x32_bf16 v[62:65], v[144:147], v[160:163], v[62:65]
	v_mfma_f32_16x16x32_bf16 v[58:61], v[144:147], v[164:167], v[58:61]
	v_mfma_f32_16x16x32_bf16 v[54:57], v[144:147], v[168:171], v[54:57]
	v_mfma_f32_16x16x32_bf16 v[50:53], v[144:147], v[232:235], v[50:53]
	s_setprio 0
	s_waitcnt lgkmcnt(0)
	s_waitcnt vmcnt(0)
	s_add_i32 s13, s13, 0x10000
	s_addk_i32 s15, 0x80
	s_cmp_eq_u32 s15, 0x30400
	s_mov_b32 s2, 0x10000
	s_barrier
	s_cbranch_scc0 .Lrot3_top_l
.Lrot3_top_n:
	v_add_u32_e32 v228, s2, v138
	v_add_u32_e32 v229, s2, v136
	ds_read_b128 v[132:135], v229 offset:0
	ds_read_b128 v[140:143], v229 offset:0x800
	ds_read_b128 v[144:147], v229 offset:0x1000
	ds_read_b128 v[148:151], v229 offset:0x1800
	ds_read_b128 v[152:155], v228 offset:0
	ds_read_b128 v[156:159], v228 offset:0x800
	s_setprio 1
	v_mfma_f32_16x16x32_bf16 v[46:49], v[236:239], v[160:163], v[46:49]
	v_mfma_f32_16x16x32_bf16 v[42:45], v[236:239], v[164:167], v[42:45]
	v_mfma_f32_16x16x32_bf16 v[38:41], v[236:239], v[168:171], v[38:41]
	v_mfma_f32_16x16x32_bf16 v[34:37], v[236:239], v[232:235], v[34:37]
	v_mfma_f32_16x16x32_bf16 v[30:33], v[240:243], v[160:163], v[30:33]
	v_mfma_f32_16x16x32_bf16 v[26:29], v[240:243], v[164:167], v[26:29]
	v_mfma_f32_16x16x32_bf16 v[22:25], v[240:243], v[168:171], v[22:25]
	v_mfma_f32_16x16x32_bf16 v[18:21], v[240:243], v[232:235], v[18:21]
	v_mfma_f32_16x16x32_bf16 v[14:17], v[244:247], v[160:163], v[14:17]
	v_mfma_f32_16x16x32_bf16 v[10:13], v[244:247], v[164:167], v[10:13]
	v_mfma_f32_16x16x32_bf16 v[6:9], v[244:247], v[168:171], v[6:9]
	v_mfma_f32_16x16x32_bf16 v[2:5], v[244:247], v[232:235], v[2:5]
	ds_read_b128 v[160:163], v228 offset:0x1000
	v_xor_b32_e32 v176, 64, v228
	s_waitcnt lgkmcnt(2)
	s_nop 0
	v_mfma_f32_16x16x32_bf16 v[126:129], v[152:155], v[132:135], v[126:129]
	v_mfma_f32_16x16x32_bf16 v[122:125], v[152:155], v[140:143], v[122:125]
	v_mfma_f32_16x16x32_bf16 v[118:121], v[152:155], v[144:147], v[118:121]
	v_mfma_f32_16x16x32_bf16 v[114:117], v[152:155], v[148:151], v[114:117]
	ds_read_b128 v[152:155], v228 offset:0x1800
	s_waitcnt lgkmcnt(2)
	s_nop 0
	v_mfma_f32_16x16x32_bf16 v[110:113], v[156:159], v[132:135], v[110:113]
	v_mfma_f32_16x16x32_bf16 v[106:109], v[156:159], v[140:143], v[106:109]
	v_mfma_f32_16x16x32_bf16 v[102:105], v[156:159], v[144:147], v[102:105]
	v_mfma_f32_16x16x32_bf16 v[98:101], v[156:159], v[148:151], v[98:101]
	ds_read_b128 v[156:159], v228 offset:0x2000
	s_waitcnt lgkmcnt(2)
	s_nop 0
	v_mfma_f32_16x16x32_bf16 v[94:97], v[160:163], v[132:135], v[94:97]
	v_mfma_f32_16x16x32_bf16 v[90:93], v[160:163], v[140:143], v[90:93]
	v_mfma_f32_16x16x32_bf16 v[86:89], v[160:163], v[144:147], v[86:89]
	v_mfma_f32_16x16x32_bf16 v[82:85], v[160:163], v[148:151], v[82:85]
	ds_read_b128 v[160:163], v228 offset:0x2800
	s_waitcnt lgkmcnt(2)
	s_nop 0
	v_mfma_f32_16x16x32_bf16 v[78:81], v[152:155], v[132:135], v[78:81]
	v_mfma_f32_16x16x32_bf16 v[74:77], v[152:155], v[140:143], v[74:77]
	v_mfma_f32_16x16x32_bf16 v[70:73], v[152:155], v[144:147], v[70:73]
	v_mfma_f32_16x16x32_bf16 v[66:69], v[152:155], v[148:151], v[66:69]
	ds_read_b128 v[152:155], v228 offset:0x3000
	s_waitcnt lgkmcnt(2)
	s_nop 0
	v_mfma_f32_16x16x32_bf16 v[62:65], v[156:159], v[132:135], v[62:65]
	v_mfma_f32_16x16x32_bf16 v[58:61], v[156:159], v[140:143], v[58:61]
	v_mfma_f32_16x16x32_bf16 v[54:57], v[156:159], v[144:147], v[54:57]
	v_mfma_f32_16x16x32_bf16 v[50:53], v[156:159], v[148:151], v[50:53]
	ds_read_b128 v[156:159], v228 offset:0x3800
	s_waitcnt lgkmcnt(2)
	v_xor_b32_e32 v0, 64, v229
	v_mfma_f32_16x16x32_bf16 v[46:49], v[160:163], v[132:135], v[46:49]
	v_mfma_f32_16x16x32_bf16 v[42:45], v[160:163], v[140:143], v[42:45]
	v_mfma_f32_16x16x32_bf16 v[38:41], v[160:163], v[144:147], v[38:41]
	v_mfma_f32_16x16x32_bf16 v[34:37], v[160:163], v[148:151], v[34:37]
	ds_read_b128 v[160:163], v0 offset:0
	ds_read_b128 v[164:167], v0 offset:0x800
	ds_read_b128 v[168:171], v0 offset:0x1000
	s_waitcnt lgkmcnt(4)
	s_nop 0
	v_mfma_f32_16x16x32_bf16 v[30:33], v[152:155], v[132:135], v[30:33]
	v_mfma_f32_16x16x32_bf16 v[26:29], v[152:155], v[140:143], v[26:29]
	v_mfma_f32_16x16x32_bf16 v[22:25], v[152:155], v[144:147], v[22:25]
	v_mfma_f32_16x16x32_bf16 v[18:21], v[152:155], v[148:151], v[18:21]
	ds_read_b128 v[232:235], v0 offset:0x1800
	ds_read_b128 v[172:175], v176 offset:0
	ds_read_b128 v[202:205], v176 offset:0x800
	s_waitcnt lgkmcnt(6)
	s_nop 0
	v_mfma_f32_16x16x32_bf16 v[14:17], v[156:159], v[132:135], v[14:17]
	v_mfma_f32_16x16x32_bf16 v[10:13], v[156:159], v[140:143], v[10:13]
	v_mfma_f32_16x16x32_bf16 v[6:9], v[156:159], v[144:147], v[6:9]
	v_mfma_f32_16x16x32_bf16 v[2:5], v[156:159], v[148:151], v[2:5]
	ds_read_b128 v[132:135], v176 offset:0x1000
	s_waitcnt lgkmcnt(2)
	s_nop 0
	v_mfma_f32_16x16x32_bf16 v[126:129], v[172:175], v[160:163], v[126:129]
	v_mfma_f32_16x16x32_bf16 v[122:125], v[172:175], v[164:167], v[122:125]
	v_mfma_f32_16x16x32_bf16 v[118:121], v[172:175], v[168:171], v[118:121]
	v_mfma_f32_16x16x32_bf16 v[114:117], v[172:175], v[232:235], v[114:117]
	ds_read_b128 v[140:143], v176 offset:0x1800
	s_waitcnt lgkmcnt(2)
	s_nop 0
	v_mfma_f32_16x16x32_bf16 v[110:113], v[202:205], v[160:163], v[110:113]
	v_mfma_f32_16x16x32_bf16 v[106:109], v[202:205], v[164:167], v[106:109]
	v_mfma_f32_16x16x32_bf16 v[102:105], v[202:205], v[168:171], v[102:105]
	v_mfma_f32_16x16x32_bf16 v[98:101], v[202:205], v[232:235], v[98:101]
	ds_read_b128 v[144:147], v176 offset:0x2000
	ds_read_b128 v[236:239], v176 offset:0x2800
	s_waitcnt lgkmcnt(3)
	s_nop 0
	v_mfma_f32_16x16x32_bf16 v[94:97], v[132:135], v[160:163], v[94:97]
	v_mfma_f32_16x16x32_bf16 v[90:93], v[132:135], v[164:167], v[90:93]
	v_mfma_f32_16x16x32_bf16 v[86:89], v[132:135], v[168:171], v[86:89]
	v_mfma_f32_16x16x32_bf16 v[82:85], v[132:135], v[232:235], v[82:85]
	ds_read_b128 v[240:243], v176 offset:0x3000
	s_waitcnt lgkmcnt(3)
	s_nop 0
	v_mfma_f32_16x16x32_bf16 v[78:81], v[140:143], v[160:163], v[78:81]
	v_mfma_f32_16x16x32_bf16 v[74:77], v[140:143], v[164:167], v[74:77]
	v_mfma_f32_16x16x32_bf16 v[70:73], v[140:143], v[168:171], v[70:73]
	v_mfma_f32_16x16x32_bf16 v[66:69], v[140:143], v[232:235], v[66:69]
	ds_read_b128 v[244:247], v176 offset:0x3800
	s_waitcnt lgkmcnt(3)
	s_nop 0
	v_mfma_f32_16x16x32_bf16 v[62:65], v[144:147], v[160:163], v[62:65]
	v_mfma_f32_16x16x32_bf16 v[58:61], v[144:147], v[164:167], v[58:61]
	v_mfma_f32_16x16x32_bf16 v[54:57], v[144:147], v[168:171], v[54:57]
	v_mfma_f32_16x16x32_bf16 v[50:53], v[144:147], v[232:235], v[50:53]
	s_setprio 0
	s_waitcnt lgkmcnt(0)
	s_add_i32 s13, s13, 0x10000
	s_addk_i32 s15, 0x80
	s_barrier
	v_mfma_f32_16x16x32_bf16 v[46:49], v[236:239], v[160:163], v[46:49]
	v_mfma_f32_16x16x32_bf16 v[42:45], v[236:239], v[164:167], v[42:45]
	v_mfma_f32_16x16x32_bf16 v[38:41], v[236:239], v[168:171], v[38:41]
	v_mfma_f32_16x16x32_bf16 v[34:37], v[236:239], v[232:235], v[34:37]
	v_mfma_f32_16x16x32_bf16 v[30:33], v[240:243], v[160:163], v[30:33]
	v_mfma_f32_16x16x32_bf16 v[26:29], v[240:243], v[164:167], v[26:29]
	v_mfma_f32_16x16x32_bf16 v[22:25], v[240:243], v[168:171], v[22:25]
	v_mfma_f32_16x16x32_bf16 v[18:21], v[240:243], v[232:235], v[18:21]
	v_mfma_f32_16x16x32_bf16 v[14:17], v[244:247], v[160:163], v[14:17]
	v_mfma_f32_16x16x32_bf16 v[10:13], v[244:247], v[164:167], v[10:13]
	v_mfma_f32_16x16x32_bf16 v[6:9], v[244:247], v[168:171], v[6:9]
	v_mfma_f32_16x16x32_bf16 v[2:5], v[244:247], v[232:235], v[2:5]
	s_nop 7
	s_nop 7
	s_nop 3

.LBB0_271:
	s_cmp_eq_u32 s21, 0x60800
	s_mov_b32 s2, 0x10000
	s_and_b32 s2, s19, 0x10000
	s_xor_b32 s10, s2, 0x10000
	s_add_i32 s51, s29, s10
	s_add_i32 s52, s21, 0xfffa0000
	s_add_i32 s53, s51, 0x8000
	s_mov_b32 s10, s66
	s_mov_b32 s11, s67
	s_waitcnt lgkmcnt(0)
	v_add_u32_e32 v228, s2, v205
	v_add_u32_e32 v229, s2, v202
	ds_read_b128 v[130:133], v229 offset:0
	ds_read_b128 v[134:137], v229 offset:0x800
	ds_read_b128 v[138:141], v229 offset:0x1000
	ds_read_b128 v[142:145], v229 offset:0x1800
	ds_read_b128 v[146:149], v228 offset:0
	ds_read_b128 v[150:153], v228 offset:0x800
	s_setprio 1
	s_mov_b32 m0, s51
	s_nop 0
	buffer_load_dwordx4 v173, s[64:67], s52 offen lds
	s_mov_b32 m0, s53
	s_nop 0
	buffer_load_dwordx4 v173, s[8:11], s52 offen lds
	s_add_i32 m0, s51, 0x2000
	s_add_i32 s52, s21, 0xfffc0000
	buffer_load_dwordx4 v173, s[64:67], s52 offen lds
	s_add_i32 m0, s51, 0xa000
	s_nop 0
	buffer_load_dwordx4 v173, s[8:11], s52 offen lds
	ds_read_b128 v[154:157], v228 offset:0x1000
	v_xor_b32_e32 v177, 64, v228
	s_branch .Lrot2_mid_l
.Lrot2_top_l:
	s_and_b32 s2, s19, 0x10000
	s_xor_b32 s10, s2, 0x10000
	s_add_i32 s51, s29, s10
	s_add_i32 s52, s21, 0xfffa0000
	s_add_i32 s53, s51, 0x8000
	s_mov_b32 s10, s66
	s_mov_b32 s11, s67
	v_add_u32_e32 v228, s2, v205
	v_add_u32_e32 v229, s2, v202
	ds_read_b128 v[130:133], v229 offset:0
	ds_read_b128 v[134:137], v229 offset:0x800
	ds_read_b128 v[138:141], v229 offset:0x1000
	ds_read_b128 v[142:145], v229 offset:0x1800
	ds_read_b128 v[146:149], v228 offset:0
	ds_read_b128 v[150:153], v228 offset:0x800
	s_setprio 1
	s_mov_b32 m0, s51
	s_nop 0
	buffer_load_dwordx4 v173, s[64:67], s52 offen lds
	s_mov_b32 m0, s53
	s_nop 0
	buffer_load_dwordx4 v173, s[8:11], s52 offen lds
	v_mfma_f32_16x16x32_bf16 v[46:49], v[236:239], v[154:157], v[46:49]
	v_mfma_f32_16x16x32_bf16 v[42:45], v[236:239], v[158:161], v[42:45]
	v_mfma_f32_16x16x32_bf16 v[38:41], v[236:239], v[162:165], v[38:41]
	v_mfma_f32_16x16x32_bf16 v[34:37], v[236:239], v[232:235], v[34:37]
	s_add_i32 m0, s51, 0x2000
	s_add_i32 s52, s21, 0xfffc0000
	buffer_load_dwordx4 v173, s[64:67], s52 offen lds
	v_mfma_f32_16x16x32_bf16 v[30:33], v[240:243], v[154:157], v[30:33]
	v_mfma_f32_16x16x32_bf16 v[26:29], v[240:243], v[158:161], v[26:29]
	v_mfma_f32_16x16x32_bf16 v[22:25], v[240:243], v[162:165], v[22:25]
	v_mfma_f32_16x16x32_bf16 v[18:21], v[240:243], v[232:235], v[18:21]
	s_add_i32 m0, s51, 0xa000
	s_nop 0
	buffer_load_dwordx4 v173, s[8:11], s52 offen lds
	v_mfma_f32_16x16x32_bf16 v[14:17], v[244:247], v[154:157], v[14:17]
	v_mfma_f32_16x16x32_bf16 v[10:13], v[244:247], v[158:161], v[10:13]
	v_mfma_f32_16x16x32_bf16 v[6:9], v[244:247], v[162:165], v[6:9]
	v_mfma_f32_16x16x32_bf16 v[2:5], v[244:247], v[232:235], v[2:5]
	ds_read_b128 v[154:157], v228 offset:0x1000
	v_xor_b32_e32 v177, 64, v228
.Lrot2_mid_l:
	s_waitcnt lgkmcnt(2)
	s_nop 0
	v_mfma_f32_16x16x32_bf16 v[122:125], v[146:149], v[130:133], v[122:125]
	v_mfma_f32_16x16x32_bf16 v[126:129], v[146:149], v[134:137], v[126:129]
	v_mfma_f32_16x16x32_bf16 v[118:121], v[146:149], v[138:141], v[118:121]
	v_mfma_f32_16x16x32_bf16 v[114:117], v[146:149], v[142:145], v[114:117]
	s_add_i32 m0, s51, 0x4000
	s_add_i32 s52, s21, 0xfffe0000
	buffer_load_dwordx4 v173, s[64:67], s52 offen lds
	ds_read_b128 v[146:149], v228 offset:0x1800
	s_waitcnt lgkmcnt(2)
	s_nop 0
	v_mfma_f32_16x16x32_bf16 v[110:113], v[150:153], v[130:133], v[110:113]
	v_mfma_f32_16x16x32_bf16 v[106:109], v[150:153], v[134:137], v[106:109]
	v_mfma_f32_16x16x32_bf16 v[102:105], v[150:153], v[138:141], v[102:105]
	v_mfma_f32_16x16x32_bf16 v[98:101], v[150:153], v[142:145], v[98:101]
	s_add_i32 m0, s51, 0xc000
	s_nop 0
	buffer_load_dwordx4 v173, s[8:11], s52 offen lds
	ds_read_b128 v[150:153], v228 offset:0x2000
	s_waitcnt lgkmcnt(2)
	s_nop 0
	v_mfma_f32_16x16x32_bf16 v[94:97], v[154:157], v[130:133], v[94:97]
	v_mfma_f32_16x16x32_bf16 v[90:93], v[154:157], v[134:137], v[90:93]
	v_mfma_f32_16x16x32_bf16 v[86:89], v[154:157], v[138:141], v[86:89]
	v_mfma_f32_16x16x32_bf16 v[82:85], v[154:157], v[142:145], v[82:85]
	s_add_i32 m0, s51, 0x6000
	s_nop 0
	buffer_load_dwordx4 v173, s[64:67], s21 offen lds
	ds_read_b128 v[154:157], v228 offset:0x2800
	s_waitcnt lgkmcnt(2)
	s_nop 0
	v_mfma_f32_16x16x32_bf16 v[78:81], v[146:149], v[130:133], v[78:81]
	v_mfma_f32_16x16x32_bf16 v[74:77], v[146:149], v[134:137], v[74:77]
	v_mfma_f32_16x16x32_bf16 v[70:73], v[146:149], v[138:141], v[70:73]
	v_mfma_f32_16x16x32_bf16 v[66:69], v[146:149], v[142:145], v[66:69]
	s_add_i32 m0, s51, 0xe000
	s_nop 0
	buffer_load_dwordx4 v173, s[8:11], s21 offen lds
	ds_read_b128 v[146:149], v228 offset:0x3000
	s_waitcnt lgkmcnt(2)
	s_nop 0
	v_mfma_f32_16x16x32_bf16 v[62:65], v[150:153], v[130:133], v[62:65]
	v_mfma_f32_16x16x32_bf16 v[58:61], v[150:153], v[134:137], v[58:61]
	v_mfma_f32_16x16x32_bf16 v[54:57], v[150:153], v[138:141], v[54:57]
	v_mfma_f32_16x16x32_bf16 v[50:53], v[150:153], v[142:145], v[50:53]
	ds_read_b128 v[150:153], v228 offset:0x3800
	s_waitcnt lgkmcnt(2)
	v_xor_b32_e32 v0, 64, v229
	v_mfma_f32_16x16x32_bf16 v[46:49], v[154:157], v[130:133], v[46:49]
	v_mfma_f32_16x16x32_bf16 v[42:45], v[154:157], v[134:137], v[42:45]
	v_mfma_f32_16x16x32_bf16 v[38:41], v[154:157], v[138:141], v[38:41]
	v_mfma_f32_16x16x32_bf16 v[34:37], v[154:157], v[142:145], v[34:37]
	ds_read_b128 v[154:157], v0 offset:0
	ds_read_b128 v[158:161], v0 offset:0x800
	ds_read_b128 v[162:165], v0 offset:0x1000
	s_waitcnt lgkmcnt(4)
	s_nop 0
	v_mfma_f32_16x16x32_bf16 v[30:33], v[146:149], v[130:133], v[30:33]
	v_mfma_f32_16x16x32_bf16 v[26:29], v[146:149], v[134:137], v[26:29]
	v_mfma_f32_16x16x32_bf16 v[22:25], v[146:149], v[138:141], v[22:25]
	v_mfma_f32_16x16x32_bf16 v[18:21], v[146:149], v[142:145], v[18:21]
	ds_read_b128 v[232:235], v0 offset:0x1800
	ds_read_b128 v[166:169], v177 offset:0
	ds_read_b128 v[206:209], v177 offset:0x800
	s_waitcnt lgkmcnt(6)
	s_nop 0
	v_mfma_f32_16x16x32_bf16 v[14:17], v[150:153], v[130:133], v[14:17]
	v_mfma_f32_16x16x32_bf16 v[10:13], v[150:153], v[134:137], v[10:13]
	v_mfma_f32_16x16x32_bf16 v[6:9], v[150:153], v[138:141], v[6:9]
	v_mfma_f32_16x16x32_bf16 v[2:5], v[150:153], v[142:145], v[2:5]
	ds_read_b128 v[130:133], v177 offset:0x1000
	s_waitcnt lgkmcnt(2)
	s_nop 0
	v_mfma_f32_16x16x32_bf16 v[122:125], v[166:169], v[154:157], v[122:125]
	v_mfma_f32_16x16x32_bf16 v[126:129], v[166:169], v[158:161], v[126:129]
	v_mfma_f32_16x16x32_bf16 v[118:121], v[166:169], v[162:165], v[118:121]
	v_mfma_f32_16x16x32_bf16 v[114:117], v[166:169], v[232:235], v[114:117]
	ds_read_b128 v[134:137], v177 offset:0x1800
	s_waitcnt lgkmcnt(2)
	s_nop 0
	v_mfma_f32_16x16x32_bf16 v[110:113], v[206:209], v[154:157], v[110:113]
	v_mfma_f32_16x16x32_bf16 v[106:109], v[206:209], v[158:161], v[106:109]
	v_mfma_f32_16x16x32_bf16 v[102:105], v[206:209], v[162:165], v[102:105]
	v_mfma_f32_16x16x32_bf16 v[98:101], v[206:209], v[232:235], v[98:101]
	ds_read_b128 v[138:141], v177 offset:0x2000
	ds_read_b128 v[236:239], v177 offset:0x2800
	s_waitcnt lgkmcnt(3)
	s_nop 0
	v_mfma_f32_16x16x32_bf16 v[94:97], v[130:133], v[154:157], v[94:97]
	v_mfma_f32_16x16x32_bf16 v[90:93], v[130:133], v[158:161], v[90:93]
	v_mfma_f32_16x16x32_bf16 v[86:89], v[130:133], v[162:165], v[86:89]
	v_mfma_f32_16x16x32_bf16 v[82:85], v[130:133], v[232:235], v[82:85]
	ds_read_b128 v[240:243], v177 offset:0x3000
	s_waitcnt lgkmcnt(3)
	s_nop 0
	v_mfma_f32_16x16x32_bf16 v[78:81], v[134:137], v[154:157], v[78:81]
	v_mfma_f32_16x16x32_bf16 v[74:77], v[134:137], v[158:161], v[74:77]
	v_mfma_f32_16x16x32_bf16 v[70:73], v[134:137], v[162:165], v[70:73]
	v_mfma_f32_16x16x32_bf16 v[66:69], v[134:137], v[232:235], v[66:69]
	ds_read_b128 v[244:247], v177 offset:0x3800
	s_waitcnt lgkmcnt(3)
	s_nop 0
	v_mfma_f32_16x16x32_bf16 v[62:65], v[138:141], v[154:157], v[62:65]
	v_mfma_f32_16x16x32_bf16 v[58:61], v[138:141], v[158:161], v[58:61]
	v_mfma_f32_16x16x32_bf16 v[54:57], v[138:141], v[162:165], v[54:57]
	v_mfma_f32_16x16x32_bf16 v[50:53], v[138:141], v[232:235], v[50:53]
	s_setprio 0
	s_waitcnt lgkmcnt(0)
	s_waitcnt vmcnt(0)
	s_add_i32 s19, s19, 0x10000
	s_addk_i32 s21, 0x80
	s_cmp_eq_u32 s21, 0x60800
	s_mov_b32 s2, 0x10000
	s_barrier
	s_cbranch_scc0 .Lrot2_top_l
.Lrot2_top_n:
	v_add_u32_e32 v228, s2, v205
	v_add_u32_e32 v229, s2, v202
	ds_read_b128 v[130:133], v229 offset:0
	ds_read_b128 v[134:137], v229 offset:0x800
	ds_read_b128 v[138:141], v229 offset:0x1000
	ds_read_b128 v[142:145], v229 offset:0x1800
	ds_read_b128 v[146:149], v228 offset:0
	ds_read_b128 v[150:153], v228 offset:0x800
	s_setprio 1
	v_mfma_f32_16x16x32_bf16 v[46:49], v[236:239], v[154:157], v[46:49]
	v_mfma_f32_16x16x32_bf16 v[42:45], v[236:239], v[158:161], v[42:45]
	v_mfma_f32_16x16x32_bf16 v[38:41], v[236:239], v[162:165], v[38:41]
	v_mfma_f32_16x16x32_bf16 v[34:37], v[236:239], v[232:235], v[34:37]
	v_mfma_f32_16x16x32_bf16 v[30:33], v[240:243], v[154:157], v[30:33]
	v_mfma_f32_16x16x32_bf16 v[26:29], v[240:243], v[158:161], v[26:29]
	v_mfma_f32_16x16x32_bf16 v[22:25], v[240:243], v[162:165], v[22:25]
	v_mfma_f32_16x16x32_bf16 v[18:21], v[240:243], v[232:235], v[18:21]
	v_mfma_f32_16x16x32_bf16 v[14:17], v[244:247], v[154:157], v[14:17]
	v_mfma_f32_16x16x32_bf16 v[10:13], v[244:247], v[158:161], v[10:13]
	v_mfma_f32_16x16x32_bf16 v[6:9], v[244:247], v[162:165], v[6:9]
	v_mfma_f32_16x16x32_bf16 v[2:5], v[244:247], v[232:235], v[2:5]
	ds_read_b128 v[154:157], v228 offset:0x1000
	v_xor_b32_e32 v177, 64, v228
	s_waitcnt lgkmcnt(2)
	s_nop 0
	v_mfma_f32_16x16x32_bf16 v[122:125], v[146:149], v[130:133], v[122:125]
	v_mfma_f32_16x16x32_bf16 v[126:129], v[146:149], v[134:137], v[126:129]
	v_mfma_f32_16x16x32_bf16 v[118:121], v[146:149], v[138:141], v[118:121]
	v_mfma_f32_16x16x32_bf16 v[114:117], v[146:149], v[142:145], v[114:117]
	ds_read_b128 v[146:149], v228 offset:0x1800
	s_waitcnt lgkmcnt(2)
	s_nop 0
	v_mfma_f32_16x16x32_bf16 v[110:113], v[150:153], v[130:133], v[110:113]
	v_mfma_f32_16x16x32_bf16 v[106:109], v[150:153], v[134:137], v[106:109]
	v_mfma_f32_16x16x32_bf16 v[102:105], v[150:153], v[138:141], v[102:105]
	v_mfma_f32_16x16x32_bf16 v[98:101], v[150:153], v[142:145], v[98:101]
	ds_read_b128 v[150:153], v228 offset:0x2000
	s_waitcnt lgkmcnt(2)
	s_nop 0
	v_mfma_f32_16x16x32_bf16 v[94:97], v[154:157], v[130:133], v[94:97]
	v_mfma_f32_16x16x32_bf16 v[90:93], v[154:157], v[134:137], v[90:93]
	v_mfma_f32_16x16x32_bf16 v[86:89], v[154:157], v[138:141], v[86:89]
	v_mfma_f32_16x16x32_bf16 v[82:85], v[154:157], v[142:145], v[82:85]
	ds_read_b128 v[154:157], v228 offset:0x2800
	s_waitcnt lgkmcnt(2)
	s_nop 0
	v_mfma_f32_16x16x32_bf16 v[78:81], v[146:149], v[130:133], v[78:81]
	v_mfma_f32_16x16x32_bf16 v[74:77], v[146:149], v[134:137], v[74:77]
	v_mfma_f32_16x16x32_bf16 v[70:73], v[146:149], v[138:141], v[70:73]
	v_mfma_f32_16x16x32_bf16 v[66:69], v[146:149], v[142:145], v[66:69]
	ds_read_b128 v[146:149], v228 offset:0x3000
	s_waitcnt lgkmcnt(2)
	s_nop 0
	v_mfma_f32_16x16x32_bf16 v[62:65], v[150:153], v[130:133], v[62:65]
	v_mfma_f32_16x16x32_bf16 v[58:61], v[150:153], v[134:137], v[58:61]
	v_mfma_f32_16x16x32_bf16 v[54:57], v[150:153], v[138:141], v[54:57]
	v_mfma_f32_16x16x32_bf16 v[50:53], v[150:153], v[142:145], v[50:53]
	ds_read_b128 v[150:153], v228 offset:0x3800
	s_waitcnt lgkmcnt(2)
	v_xor_b32_e32 v0, 64, v229
	v_mfma_f32_16x16x32_bf16 v[46:49], v[154:157], v[130:133], v[46:49]
	v_mfma_f32_16x16x32_bf16 v[42:45], v[154:157], v[134:137], v[42:45]
	v_mfma_f32_16x16x32_bf16 v[38:41], v[154:157], v[138:141], v[38:41]
	v_mfma_f32_16x16x32_bf16 v[34:37], v[154:157], v[142:145], v[34:37]
	ds_read_b128 v[154:157], v0 offset:0
	ds_read_b128 v[158:161], v0 offset:0x800
	ds_read_b128 v[162:165], v0 offset:0x1000
	s_waitcnt lgkmcnt(4)
	s_nop 0
	v_mfma_f32_16x16x32_bf16 v[30:33], v[146:149], v[130:133], v[30:33]
	v_mfma_f32_16x16x32_bf16 v[26:29], v[146:149], v[134:137], v[26:29]
	v_mfma_f32_16x16x32_bf16 v[22:25], v[146:149], v[138:141], v[22:25]
	v_mfma_f32_16x16x32_bf16 v[18:21], v[146:149], v[142:145], v[18:21]
	ds_read_b128 v[232:235], v0 offset:0x1800
	ds_read_b128 v[166:169], v177 offset:0
	ds_read_b128 v[206:209], v177 offset:0x800
	s_waitcnt lgkmcnt(6)
	s_nop 0
	v_mfma_f32_16x16x32_bf16 v[14:17], v[150:153], v[130:133], v[14:17]
	v_mfma_f32_16x16x32_bf16 v[10:13], v[150:153], v[134:137], v[10:13]
	v_mfma_f32_16x16x32_bf16 v[6:9], v[150:153], v[138:141], v[6:9]
	v_mfma_f32_16x16x32_bf16 v[2:5], v[150:153], v[142:145], v[2:5]
	ds_read_b128 v[130:133], v177 offset:0x1000
	s_waitcnt lgkmcnt(2)
	s_nop 0
	v_mfma_f32_16x16x32_bf16 v[122:125], v[166:169], v[154:157], v[122:125]
	v_mfma_f32_16x16x32_bf16 v[126:129], v[166:169], v[158:161], v[126:129]
	v_mfma_f32_16x16x32_bf16 v[118:121], v[166:169], v[162:165], v[118:121]
	v_mfma_f32_16x16x32_bf16 v[114:117], v[166:169], v[232:235], v[114:117]
	ds_read_b128 v[134:137], v177 offset:0x1800
	s_waitcnt lgkmcnt(2)
	s_nop 0
	v_mfma_f32_16x16x32_bf16 v[110:113], v[206:209], v[154:157], v[110:113]
	v_mfma_f32_16x16x32_bf16 v[106:109], v[206:209], v[158:161], v[106:109]
	v_mfma_f32_16x16x32_bf16 v[102:105], v[206:209], v[162:165], v[102:105]
	v_mfma_f32_16x16x32_bf16 v[98:101], v[206:209], v[232:235], v[98:101]
	ds_read_b128 v[138:141], v177 offset:0x2000
	ds_read_b128 v[236:239], v177 offset:0x2800
	s_waitcnt lgkmcnt(3)
	s_nop 0
	v_mfma_f32_16x16x32_bf16 v[94:97], v[130:133], v[154:157], v[94:97]
	v_mfma_f32_16x16x32_bf16 v[90:93], v[130:133], v[158:161], v[90:93]
	v_mfma_f32_16x16x32_bf16 v[86:89], v[130:133], v[162:165], v[86:89]
	v_mfma_f32_16x16x32_bf16 v[82:85], v[130:133], v[232:235], v[82:85]
	ds_read_b128 v[240:243], v177 offset:0x3000
	s_waitcnt lgkmcnt(3)
	s_nop 0
	v_mfma_f32_16x16x32_bf16 v[78:81], v[134:137], v[154:157], v[78:81]
	v_mfma_f32_16x16x32_bf16 v[74:77], v[134:137], v[158:161], v[74:77]
	v_mfma_f32_16x16x32_bf16 v[70:73], v[134:137], v[162:165], v[70:73]
	v_mfma_f32_16x16x32_bf16 v[66:69], v[134:137], v[232:235], v[66:69]
	ds_read_b128 v[244:247], v177 offset:0x3800
	s_waitcnt lgkmcnt(3)
	s_nop 0
	v_mfma_f32_16x16x32_bf16 v[62:65], v[138:141], v[154:157], v[62:65]
	v_mfma_f32_16x16x32_bf16 v[58:61], v[138:141], v[158:161], v[58:61]
	v_mfma_f32_16x16x32_bf16 v[54:57], v[138:141], v[162:165], v[54:57]
	v_mfma_f32_16x16x32_bf16 v[50:53], v[138:141], v[232:235], v[50:53]
	s_setprio 0
	s_waitcnt lgkmcnt(0)
	s_add_i32 s19, s19, 0x10000
	s_addk_i32 s21, 0x80
	s_barrier
	v_mfma_f32_16x16x32_bf16 v[46:49], v[236:239], v[154:157], v[46:49]
	v_mfma_f32_16x16x32_bf16 v[42:45], v[236:239], v[158:161], v[42:45]
	v_mfma_f32_16x16x32_bf16 v[38:41], v[236:239], v[162:165], v[38:41]
	v_mfma_f32_16x16x32_bf16 v[34:37], v[236:239], v[232:235], v[34:37]
	v_mfma_f32_16x16x32_bf16 v[30:33], v[240:243], v[154:157], v[30:33]
	v_mfma_f32_16x16x32_bf16 v[26:29], v[240:243], v[158:161], v[26:29]
	v_mfma_f32_16x16x32_bf16 v[22:25], v[240:243], v[162:165], v[22:25]
	v_mfma_f32_16x16x32_bf16 v[18:21], v[240:243], v[232:235], v[18:21]
	v_mfma_f32_16x16x32_bf16 v[14:17], v[244:247], v[154:157], v[14:17]
	v_mfma_f32_16x16x32_bf16 v[10:13], v[244:247], v[158:161], v[10:13]
	v_mfma_f32_16x16x32_bf16 v[6:9], v[244:247], v[162:165], v[6:9]
	v_mfma_f32_16x16x32_bf16 v[2:5], v[244:247], v[232:235], v[2:5]
	s_nop 7
	s_nop 7
	s_nop 3

.LBB0_296:
	s_and_b32 s2, s44, 0x10000
	s_cmp_ge_u32 s41, s24
	s_xor_b32 s14, s2, 0x10000
	s_add_i32 s46, s26, s14
	s_add_i32 s47, s46, 0x8000
	s_mov_b32 s14, s66
	s_mov_b32 s15, s67
	s_waitcnt lgkmcnt(0)
	v_add_u32_e32 v228, s2, v143
	v_add_u32_e32 v229, s2, v133
	ds_read_b128 v[134:137], v229 offset:0
	ds_read_b128 v[138:141], v229 offset:0x800
	ds_read_b128 v[144:147], v229 offset:0x1000
	ds_read_b128 v[148:151], v229 offset:0x1800
	ds_read_b128 v[152:155], v228 offset:0
	ds_read_b128 v[156:159], v228 offset:0x800
	s_setprio 1
	s_mov_b32 m0, s46
	s_nop 0
	buffer_load_dwordx4 v131, s[64:67], s45 offen lds
	s_mov_b32 m0, s47
	s_add_i32 s47, s27, s45
	buffer_load_dwordx4 v131, s[12:15], s45 offen lds
	s_add_i32 m0, s46, 0x2000
	s_nop 0
	buffer_load_dwordx4 v131, s[64:67], s47 offen lds
	s_add_i32 m0, s46, 0xa000
	s_nop 0
	buffer_load_dwordx4 v131, s[12:15], s47 offen lds
	ds_read_b128 v[160:163], v228 offset:0x1000
	v_xor_b32_e32 v176, 64, v228
	s_branch .Lrot1_mid_l
.Lrot1_top_l:
	s_xor_b32 s14, s2, 0x10000
	s_add_i32 s46, s26, s14
	s_add_i32 s47, s46, 0x8000
	s_mov_b32 s14, s66
	s_mov_b32 s15, s67
	v_add_u32_e32 v228, s2, v143
	v_add_u32_e32 v229, s2, v133
	ds_read_b128 v[134:137], v229 offset:0
	ds_read_b128 v[138:141], v229 offset:0x800
	ds_read_b128 v[144:147], v229 offset:0x1000
	ds_read_b128 v[148:151], v229 offset:0x1800
	ds_read_b128 v[152:155], v228 offset:0
	ds_read_b128 v[156:159], v228 offset:0x800
	s_setprio 1
	s_mov_b32 m0, s46
	s_nop 0
	buffer_load_dwordx4 v131, s[64:67], s45 offen lds
	s_mov_b32 m0, s47
	s_add_i32 s47, s27, s45
	buffer_load_dwordx4 v131, s[12:15], s45 offen lds
	v_mfma_f32_16x16x32_bf16 v[46:49], v[236:239], v[160:163], v[46:49]
	v_mfma_f32_16x16x32_bf16 v[42:45], v[236:239], v[164:167], v[42:45]
	v_mfma_f32_16x16x32_bf16 v[38:41], v[236:239], v[168:171], v[38:41]
	v_mfma_f32_16x16x32_bf16 v[34:37], v[236:239], v[232:235], v[34:37]
	s_add_i32 m0, s46, 0x2000
	s_nop 0
	buffer_load_dwordx4 v131, s[64:67], s47 offen lds
	v_mfma_f32_16x16x32_bf16 v[30:33], v[240:243], v[160:163], v[30:33]
	v_mfma_f32_16x16x32_bf16 v[26:29], v[240:243], v[164:167], v[26:29]
	v_mfma_f32_16x16x32_bf16 v[22:25], v[240:243], v[168:171], v[22:25]
	v_mfma_f32_16x16x32_bf16 v[18:21], v[240:243], v[232:235], v[18:21]
	s_add_i32 m0, s46, 0xa000
	s_nop 0
	buffer_load_dwordx4 v131, s[12:15], s47 offen lds
	v_mfma_f32_16x16x32_bf16 v[14:17], v[244:247], v[160:163], v[14:17]
	v_mfma_f32_16x16x32_bf16 v[10:13], v[244:247], v[164:167], v[10:13]
	v_mfma_f32_16x16x32_bf16 v[6:9], v[244:247], v[168:171], v[6:9]
	v_mfma_f32_16x16x32_bf16 v[2:5], v[244:247], v[232:235], v[2:5]
	ds_read_b128 v[160:163], v228 offset:0x1000
	v_xor_b32_e32 v176, 64, v228
.Lrot1_mid_l:
	s_waitcnt lgkmcnt(2)
	s_nop 0
	v_mfma_f32_16x16x32_bf16 v[126:129], v[152:155], v[134:137], v[126:129]
	v_mfma_f32_16x16x32_bf16 v[122:125], v[152:155], v[138:141], v[122:125]
	v_mfma_f32_16x16x32_bf16 v[118:121], v[152:155], v[144:147], v[118:121]
	v_mfma_f32_16x16x32_bf16 v[114:117], v[152:155], v[148:151], v[114:117]
	s_add_i32 m0, s46, 0x4000
	s_add_i32 s47, s34, s45
	buffer_load_dwordx4 v131, s[64:67], s47 offen lds
	ds_read_b128 v[152:155], v228 offset:0x1800
	s_waitcnt lgkmcnt(2)
	s_nop 0
	v_mfma_f32_16x16x32_bf16 v[110:113], v[156:159], v[134:137], v[110:113]
	v_mfma_f32_16x16x32_bf16 v[106:109], v[156:159], v[138:141], v[106:109]
	v_mfma_f32_16x16x32_bf16 v[102:105], v[156:159], v[144:147], v[102:105]
	v_mfma_f32_16x16x32_bf16 v[98:101], v[156:159], v[148:151], v[98:101]
	s_add_i32 m0, s46, 0xc000
	s_nop 0
	buffer_load_dwordx4 v131, s[12:15], s47 offen lds
	ds_read_b128 v[156:159], v228 offset:0x2000
	s_waitcnt lgkmcnt(2)
	s_nop 0
	v_mfma_f32_16x16x32_bf16 v[94:97], v[160:163], v[134:137], v[94:97]
	v_mfma_f32_16x16x32_bf16 v[90:93], v[160:163], v[138:141], v[90:93]
	v_mfma_f32_16x16x32_bf16 v[86:89], v[160:163], v[144:147], v[86:89]
	v_mfma_f32_16x16x32_bf16 v[82:85], v[160:163], v[148:151], v[82:85]
	s_add_i32 m0, s46, 0x6000
	s_add_i32 s47, s37, s45
	buffer_load_dwordx4 v131, s[64:67], s47 offen lds
	ds_read_b128 v[160:163], v228 offset:0x2800
	s_waitcnt lgkmcnt(2)
	s_nop 0
	v_mfma_f32_16x16x32_bf16 v[78:81], v[152:155], v[134:137], v[78:81]
	v_mfma_f32_16x16x32_bf16 v[74:77], v[152:155], v[138:141], v[74:77]
	v_mfma_f32_16x16x32_bf16 v[70:73], v[152:155], v[144:147], v[70:73]
	v_mfma_f32_16x16x32_bf16 v[66:69], v[152:155], v[148:151], v[66:69]
	s_add_i32 m0, s46, 0xe000
	s_nop 0
	buffer_load_dwordx4 v131, s[12:15], s47 offen lds
	ds_read_b128 v[152:155], v228 offset:0x3000
	s_waitcnt lgkmcnt(2)
	s_nop 0
	v_mfma_f32_16x16x32_bf16 v[62:65], v[156:159], v[134:137], v[62:65]
	v_mfma_f32_16x16x32_bf16 v[58:61], v[156:159], v[138:141], v[58:61]
	v_mfma_f32_16x16x32_bf16 v[54:57], v[156:159], v[144:147], v[54:57]
	v_mfma_f32_16x16x32_bf16 v[50:53], v[156:159], v[148:151], v[50:53]
	ds_read_b128 v[156:159], v228 offset:0x3800
	s_waitcnt lgkmcnt(2)
	v_xor_b32_e32 v0, 64, v229
	v_mfma_f32_16x16x32_bf16 v[46:49], v[160:163], v[134:137], v[46:49]
	v_mfma_f32_16x16x32_bf16 v[42:45], v[160:163], v[138:141], v[42:45]
	v_mfma_f32_16x16x32_bf16 v[38:41], v[160:163], v[144:147], v[38:41]
	v_mfma_f32_16x16x32_bf16 v[34:37], v[160:163], v[148:151], v[34:37]
	ds_read_b128 v[160:163], v0 offset:0
	ds_read_b128 v[164:167], v0 offset:0x800
	ds_read_b128 v[168:171], v0 offset:0x1000
	s_waitcnt lgkmcnt(4)
	s_nop 0
	v_mfma_f32_16x16x32_bf16 v[30:33], v[152:155], v[134:137], v[30:33]
	v_mfma_f32_16x16x32_bf16 v[26:29], v[152:155], v[138:141], v[26:29]
	v_mfma_f32_16x16x32_bf16 v[22:25], v[152:155], v[144:147], v[22:25]
	v_mfma_f32_16x16x32_bf16 v[18:21], v[152:155], v[148:151], v[18:21]
	ds_read_b128 v[232:235], v0 offset:0x1800
	ds_read_b128 v[172:175], v176 offset:0
	ds_read_b128 v[202:205], v176 offset:0x800
	s_waitcnt lgkmcnt(6)
	s_nop 0
	v_mfma_f32_16x16x32_bf16 v[14:17], v[156:159], v[134:137], v[14:17]
	v_mfma_f32_16x16x32_bf16 v[10:13], v[156:159], v[138:141], v[10:13]
	v_mfma_f32_16x16x32_bf16 v[6:9], v[156:159], v[144:147], v[6:9]
	v_mfma_f32_16x16x32_bf16 v[2:5], v[156:159], v[148:151], v[2:5]
	ds_read_b128 v[134:137], v176 offset:0x1000
	s_waitcnt lgkmcnt(2)
	s_nop 0
	v_mfma_f32_16x16x32_bf16 v[126:129], v[172:175], v[160:163], v[126:129]
	v_mfma_f32_16x16x32_bf16 v[122:125], v[172:175], v[164:167], v[122:125]
	v_mfma_f32_16x16x32_bf16 v[118:121], v[172:175], v[168:171], v[118:121]
	v_mfma_f32_16x16x32_bf16 v[114:117], v[172:175], v[232:235], v[114:117]
	ds_read_b128 v[138:141], v176 offset:0x1800
	s_waitcnt lgkmcnt(2)
	s_nop 0
	v_mfma_f32_16x16x32_bf16 v[110:113], v[202:205], v[160:163], v[110:113]
	v_mfma_f32_16x16x32_bf16 v[106:109], v[202:205], v[164:167], v[106:109]
	v_mfma_f32_16x16x32_bf16 v[102:105], v[202:205], v[168:171], v[102:105]
	v_mfma_f32_16x16x32_bf16 v[98:101], v[202:205], v[232:235], v[98:101]
	ds_read_b128 v[144:147], v176 offset:0x2000
	ds_read_b128 v[236:239], v176 offset:0x2800
	s_waitcnt lgkmcnt(3)
	s_nop 0
	v_mfma_f32_16x16x32_bf16 v[94:97], v[134:137], v[160:163], v[94:97]
	v_mfma_f32_16x16x32_bf16 v[90:93], v[134:137], v[164:167], v[90:93]
	v_mfma_f32_16x16x32_bf16 v[86:89], v[134:137], v[168:171], v[86:89]
	v_mfma_f32_16x16x32_bf16 v[82:85], v[134:137], v[232:235], v[82:85]
	ds_read_b128 v[240:243], v176 offset:0x3000
	s_waitcnt lgkmcnt(3)
	s_nop 0
	v_mfma_f32_16x16x32_bf16 v[78:81], v[138:141], v[160:163], v[78:81]
	v_mfma_f32_16x16x32_bf16 v[74:77], v[138:141], v[164:167], v[74:77]
	v_mfma_f32_16x16x32_bf16 v[70:73], v[138:141], v[168:171], v[70:73]
	v_mfma_f32_16x16x32_bf16 v[66:69], v[138:141], v[232:235], v[66:69]
	ds_read_b128 v[244:247], v176 offset:0x3800
	s_waitcnt lgkmcnt(3)
	s_nop 0
	v_mfma_f32_16x16x32_bf16 v[62:65], v[144:147], v[160:163], v[62:65]
	v_mfma_f32_16x16x32_bf16 v[58:61], v[144:147], v[164:167], v[58:61]
	v_mfma_f32_16x16x32_bf16 v[54:57], v[144:147], v[168:171], v[54:57]
	v_mfma_f32_16x16x32_bf16 v[50:53], v[144:147], v[232:235], v[50:53]
	s_setprio 0
	s_waitcnt lgkmcnt(0)
	s_waitcnt vmcnt(0)
	s_add_i32 s44, s44, 0x10000
	s_addk_i32 s45, 0x80
	s_add_i32 s41, s41, 1
	s_and_b32 s2, s44, 0x10000
	s_cmp_ge_u32 s41, s24
	s_barrier
	s_cbranch_scc0 .Lrot1_top_l
.Lrot1_top_n:
	v_add_u32_e32 v228, s2, v143
	v_add_u32_e32 v229, s2, v133
	ds_read_b128 v[134:137], v229 offset:0
	ds_read_b128 v[138:141], v229 offset:0x800
	ds_read_b128 v[144:147], v229 offset:0x1000
	ds_read_b128 v[148:151], v229 offset:0x1800
	ds_read_b128 v[152:155], v228 offset:0
	ds_read_b128 v[156:159], v228 offset:0x800
	s_setprio 1
	v_mfma_f32_16x16x32_bf16 v[46:49], v[236:239], v[160:163], v[46:49]
	v_mfma_f32_16x16x32_bf16 v[42:45], v[236:239], v[164:167], v[42:45]
	v_mfma_f32_16x16x32_bf16 v[38:41], v[236:239], v[168:171], v[38:41]
	v_mfma_f32_16x16x32_bf16 v[34:37], v[236:239], v[232:235], v[34:37]
	v_mfma_f32_16x16x32_bf16 v[30:33], v[240:243], v[160:163], v[30:33]
	v_mfma_f32_16x16x32_bf16 v[26:29], v[240:243], v[164:167], v[26:29]
	v_mfma_f32_16x16x32_bf16 v[22:25], v[240:243], v[168:171], v[22:25]
	v_mfma_f32_16x16x32_bf16 v[18:21], v[240:243], v[232:235], v[18:21]
	v_mfma_f32_16x16x32_bf16 v[14:17], v[244:247], v[160:163], v[14:17]
	v_mfma_f32_16x16x32_bf16 v[10:13], v[244:247], v[164:167], v[10:13]
	v_mfma_f32_16x16x32_bf16 v[6:9], v[244:247], v[168:171], v[6:9]
	v_mfma_f32_16x16x32_bf16 v[2:5], v[244:247], v[232:235], v[2:5]
	ds_read_b128 v[160:163], v228 offset:0x1000
	v_xor_b32_e32 v176, 64, v228
	s_waitcnt lgkmcnt(2)
	s_nop 0
	v_mfma_f32_16x16x32_bf16 v[126:129], v[152:155], v[134:137], v[126:129]
	v_mfma_f32_16x16x32_bf16 v[122:125], v[152:155], v[138:141], v[122:125]
	v_mfma_f32_16x16x32_bf16 v[118:121], v[152:155], v[144:147], v[118:121]
	v_mfma_f32_16x16x32_bf16 v[114:117], v[152:155], v[148:151], v[114:117]
	ds_read_b128 v[152:155], v228 offset:0x1800
	s_waitcnt lgkmcnt(2)
	s_nop 0
	v_mfma_f32_16x16x32_bf16 v[110:113], v[156:159], v[134:137], v[110:113]
	v_mfma_f32_16x16x32_bf16 v[106:109], v[156:159], v[138:141], v[106:109]
	v_mfma_f32_16x16x32_bf16 v[102:105], v[156:159], v[144:147], v[102:105]
	v_mfma_f32_16x16x32_bf16 v[98:101], v[156:159], v[148:151], v[98:101]
	ds_read_b128 v[156:159], v228 offset:0x2000
	s_waitcnt lgkmcnt(2)
	s_nop 0
	v_mfma_f32_16x16x32_bf16 v[94:97], v[160:163], v[134:137], v[94:97]
	v_mfma_f32_16x16x32_bf16 v[90:93], v[160:163], v[138:141], v[90:93]
	v_mfma_f32_16x16x32_bf16 v[86:89], v[160:163], v[144:147], v[86:89]
	v_mfma_f32_16x16x32_bf16 v[82:85], v[160:163], v[148:151], v[82:85]
	ds_read_b128 v[160:163], v228 offset:0x2800
	s_waitcnt lgkmcnt(2)
	s_nop 0
	v_mfma_f32_16x16x32_bf16 v[78:81], v[152:155], v[134:137], v[78:81]
	v_mfma_f32_16x16x32_bf16 v[74:77], v[152:155], v[138:141], v[74:77]
	v_mfma_f32_16x16x32_bf16 v[70:73], v[152:155], v[144:147], v[70:73]
	v_mfma_f32_16x16x32_bf16 v[66:69], v[152:155], v[148:151], v[66:69]
	ds_read_b128 v[152:155], v228 offset:0x3000
	s_waitcnt lgkmcnt(2)
	s_nop 0
	v_mfma_f32_16x16x32_bf16 v[62:65], v[156:159], v[134:137], v[62:65]
	v_mfma_f32_16x16x32_bf16 v[58:61], v[156:159], v[138:141], v[58:61]
	v_mfma_f32_16x16x32_bf16 v[54:57], v[156:159], v[144:147], v[54:57]
	v_mfma_f32_16x16x32_bf16 v[50:53], v[156:159], v[148:151], v[50:53]
	ds_read_b128 v[156:159], v228 offset:0x3800
	s_waitcnt lgkmcnt(2)
	v_xor_b32_e32 v0, 64, v229
	v_mfma_f32_16x16x32_bf16 v[46:49], v[160:163], v[134:137], v[46:49]
	v_mfma_f32_16x16x32_bf16 v[42:45], v[160:163], v[138:141], v[42:45]
	v_mfma_f32_16x16x32_bf16 v[38:41], v[160:163], v[144:147], v[38:41]
	v_mfma_f32_16x16x32_bf16 v[34:37], v[160:163], v[148:151], v[34:37]
	ds_read_b128 v[160:163], v0 offset:0
	ds_read_b128 v[164:167], v0 offset:0x800
	ds_read_b128 v[168:171], v0 offset:0x1000
	s_waitcnt lgkmcnt(4)
	s_nop 0
	v_mfma_f32_16x16x32_bf16 v[30:33], v[152:155], v[134:137], v[30:33]
	v_mfma_f32_16x16x32_bf16 v[26:29], v[152:155], v[138:141], v[26:29]
	v_mfma_f32_16x16x32_bf16 v[22:25], v[152:155], v[144:147], v[22:25]
	v_mfma_f32_16x16x32_bf16 v[18:21], v[152:155], v[148:151], v[18:21]
	ds_read_b128 v[232:235], v0 offset:0x1800
	ds_read_b128 v[172:175], v176 offset:0
	ds_read_b128 v[202:205], v176 offset:0x800
	s_waitcnt lgkmcnt(6)
	s_nop 0
	v_mfma_f32_16x16x32_bf16 v[14:17], v[156:159], v[134:137], v[14:17]
	v_mfma_f32_16x16x32_bf16 v[10:13], v[156:159], v[138:141], v[10:13]
	v_mfma_f32_16x16x32_bf16 v[6:9], v[156:159], v[144:147], v[6:9]
	v_mfma_f32_16x16x32_bf16 v[2:5], v[156:159], v[148:151], v[2:5]
	ds_read_b128 v[134:137], v176 offset:0x1000
	s_waitcnt lgkmcnt(2)
	s_nop 0
	v_mfma_f32_16x16x32_bf16 v[126:129], v[172:175], v[160:163], v[126:129]
	v_mfma_f32_16x16x32_bf16 v[122:125], v[172:175], v[164:167], v[122:125]
	v_mfma_f32_16x16x32_bf16 v[118:121], v[172:175], v[168:171], v[118:121]
	v_mfma_f32_16x16x32_bf16 v[114:117], v[172:175], v[232:235], v[114:117]
	ds_read_b128 v[138:141], v176 offset:0x1800
	s_waitcnt lgkmcnt(2)
	s_nop 0
	v_mfma_f32_16x16x32_bf16 v[110:113], v[202:205], v[160:163], v[110:113]
	v_mfma_f32_16x16x32_bf16 v[106:109], v[202:205], v[164:167], v[106:109]
	v_mfma_f32_16x16x32_bf16 v[102:105], v[202:205], v[168:171], v[102:105]
	v_mfma_f32_16x16x32_bf16 v[98:101], v[202:205], v[232:235], v[98:101]
	ds_read_b128 v[144:147], v176 offset:0x2000
	ds_read_b128 v[236:239], v176 offset:0x2800
	s_waitcnt lgkmcnt(3)
	s_nop 0
	v_mfma_f32_16x16x32_bf16 v[94:97], v[134:137], v[160:163], v[94:97]
	v_mfma_f32_16x16x32_bf16 v[90:93], v[134:137], v[164:167], v[90:93]
	v_mfma_f32_16x16x32_bf16 v[86:89], v[134:137], v[168:171], v[86:89]
	v_mfma_f32_16x16x32_bf16 v[82:85], v[134:137], v[232:235], v[82:85]
	ds_read_b128 v[240:243], v176 offset:0x3000
	s_waitcnt lgkmcnt(3)
	s_nop 0
	v_mfma_f32_16x16x32_bf16 v[78:81], v[138:141], v[160:163], v[78:81]
	v_mfma_f32_16x16x32_bf16 v[74:77], v[138:141], v[164:167], v[74:77]
	v_mfma_f32_16x16x32_bf16 v[70:73], v[138:141], v[168:171], v[70:73]
	v_mfma_f32_16x16x32_bf16 v[66:69], v[138:141], v[232:235], v[66:69]
	ds_read_b128 v[244:247], v176 offset:0x3800
	s_waitcnt lgkmcnt(3)
	s_nop 0
	v_mfma_f32_16x16x32_bf16 v[62:65], v[144:147], v[160:163], v[62:65]
	v_mfma_f32_16x16x32_bf16 v[58:61], v[144:147], v[164:167], v[58:61]
	v_mfma_f32_16x16x32_bf16 v[54:57], v[144:147], v[168:171], v[54:57]
	v_mfma_f32_16x16x32_bf16 v[50:53], v[144:147], v[232:235], v[50:53]
	s_setprio 0
	s_waitcnt lgkmcnt(0)
	s_add_i32 s44, s44, 0x10000
	s_addk_i32 s45, 0x80
	s_add_i32 s41, s41, 1
	s_barrier
	v_mfma_f32_16x16x32_bf16 v[46:49], v[236:239], v[160:163], v[46:49]
	v_mfma_f32_16x16x32_bf16 v[42:45], v[236:239], v[164:167], v[42:45]
	v_mfma_f32_16x16x32_bf16 v[38:41], v[236:239], v[168:171], v[38:41]
	v_mfma_f32_16x16x32_bf16 v[34:37], v[236:239], v[232:235], v[34:37]
	v_mfma_f32_16x16x32_bf16 v[30:33], v[240:243], v[160:163], v[30:33]
	v_mfma_f32_16x16x32_bf16 v[26:29], v[240:243], v[164:167], v[26:29]
	v_mfma_f32_16x16x32_bf16 v[22:25], v[240:243], v[168:171], v[22:25]
	v_mfma_f32_16x16x32_bf16 v[18:21], v[240:243], v[232:235], v[18:21]
	v_mfma_f32_16x16x32_bf16 v[14:17], v[244:247], v[160:163], v[14:17]
	v_mfma_f32_16x16x32_bf16 v[10:13], v[244:247], v[164:167], v[10:13]
	v_mfma_f32_16x16x32_bf16 v[6:9], v[244:247], v[168:171], v[6:9]
	v_mfma_f32_16x16x32_bf16 v[2:5], v[244:247], v[232:235], v[2:5]
	s_nop 7
	s_nop 7
	s_nop 3

.LBB0_429:
	s_cmp_eq_u32 s15, 0x60800
	s_mov_b32 s2, 0x10000
	s_and_b32 s2, s13, 0x10000
	s_xor_b32 s10, s2, 0x10000
	s_add_i32 s35, s22, s10
	s_add_i32 s36, s15, 0xfffa0000
	s_add_i32 s37, s35, 0x8000
	s_mov_b32 s10, s66
	s_mov_b32 s11, s67
	s_waitcnt lgkmcnt(0)
	v_add_u32_e32 v228, s2, v207
	v_add_u32_e32 v229, s2, v204
	ds_read_b128 v[50:53], v229 offset:0
	ds_read_b128 v[54:57], v229 offset:0x800
	ds_read_b128 v[58:61], v229 offset:0x1000
	ds_read_b128 v[78:81], v229 offset:0x1800
	ds_read_b128 v[98:101], v228 offset:0
	ds_read_b128 v[118:121], v228 offset:0x800
	s_setprio 1
	s_mov_b32 m0, s35
	s_nop 0
	buffer_load_dwordx4 v201, s[64:67], s36 offen lds
	s_mov_b32 m0, s37
	s_nop 0
	buffer_load_dwordx4 v201, s[8:11], s36 offen lds
	s_add_i32 m0, s35, 0x2000
	s_add_i32 s36, s15, 0xfffc0000
	buffer_load_dwordx4 v201, s[64:67], s36 offen lds
	s_add_i32 m0, s35, 0xa000
	s_nop 0
	buffer_load_dwordx4 v201, s[8:11], s36 offen lds
	ds_read_b128 v[138:141], v228 offset:0x1000
	v_xor_b32_e32 v208, 64, v228
	s_branch .Lrot0_mid_l
.Lrot0_top_l:
	s_and_b32 s2, s13, 0x10000
	s_xor_b32 s10, s2, 0x10000
	s_add_i32 s35, s22, s10
	s_add_i32 s36, s15, 0xfffa0000
	s_add_i32 s37, s35, 0x8000
	s_mov_b32 s10, s66
	s_mov_b32 s11, s67
	v_add_u32_e32 v228, s2, v207
	v_add_u32_e32 v229, s2, v204
	ds_read_b128 v[50:53], v229 offset:0
	ds_read_b128 v[54:57], v229 offset:0x800
	ds_read_b128 v[58:61], v229 offset:0x1000
	ds_read_b128 v[78:81], v229 offset:0x1800
	ds_read_b128 v[98:101], v228 offset:0
	ds_read_b128 v[118:121], v228 offset:0x800
	s_setprio 1
	s_mov_b32 m0, s35
	s_nop 0
	buffer_load_dwordx4 v201, s[64:67], s36 offen lds
	s_mov_b32 m0, s37
	s_nop 0
	buffer_load_dwordx4 v201, s[8:11], s36 offen lds
	v_mfma_f32_16x16x32_bf16 v[42:45], v[232:235], v[138:141], v[42:45]
	v_mfma_f32_16x16x32_bf16 v[46:49], v[232:235], v[158:161], v[46:49]
	v_mfma_f32_16x16x32_bf16 v[34:37], v[232:235], v[162:165], v[34:37]
	v_mfma_f32_16x16x32_bf16 v[38:41], v[232:235], v[166:169], v[38:41]
	s_add_i32 m0, s35, 0x2000
	s_add_i32 s36, s15, 0xfffc0000
	buffer_load_dwordx4 v201, s[64:67], s36 offen lds
	v_mfma_f32_16x16x32_bf16 v[26:29], v[236:239], v[138:141], v[26:29]
	v_mfma_f32_16x16x32_bf16 v[30:33], v[236:239], v[158:161], v[30:33]
	v_mfma_f32_16x16x32_bf16 v[18:21], v[236:239], v[162:165], v[18:21]
	v_mfma_f32_16x16x32_bf16 v[22:25], v[236:239], v[166:169], v[22:25]
	s_add_i32 m0, s35, 0xa000
	s_nop 0
	buffer_load_dwordx4 v201, s[8:11], s36 offen lds
	v_mfma_f32_16x16x32_bf16 v[10:13], v[240:243], v[138:141], v[10:13]
	v_mfma_f32_16x16x32_bf16 v[14:17], v[240:243], v[158:161], v[14:17]
	v_mfma_f32_16x16x32_bf16 v[2:5], v[240:243], v[162:165], v[2:5]
	v_mfma_f32_16x16x32_bf16 v[6:9], v[240:243], v[166:169], v[6:9]
	ds_read_b128 v[138:141], v228 offset:0x1000
	v_xor_b32_e32 v208, 64, v228
.Lrot0_mid_l:
	s_waitcnt lgkmcnt(2)
	s_nop 0
	v_mfma_f32_16x16x32_bf16 v[150:153], v[98:101], v[50:53], v[150:153]
	v_mfma_f32_16x16x32_bf16 v[154:157], v[98:101], v[54:57], v[154:157]
	v_mfma_f32_16x16x32_bf16 v[142:145], v[98:101], v[58:61], v[142:145]
	v_mfma_f32_16x16x32_bf16 v[98:101], v[98:101], v[78:81], v[146:149]
	s_add_i32 m0, s35, 0x4000
	s_add_i32 s36, s15, 0xfffe0000
	buffer_load_dwordx4 v201, s[64:67], s36 offen lds
	ds_read_b128 v[146:149], v228 offset:0x1800
	s_waitcnt lgkmcnt(2)
	s_nop 0
	v_mfma_f32_16x16x32_bf16 v[130:133], v[118:121], v[50:53], v[130:133]
	v_mfma_f32_16x16x32_bf16 v[134:137], v[118:121], v[54:57], v[134:137]
	v_mfma_f32_16x16x32_bf16 v[122:125], v[118:121], v[58:61], v[122:125]
	v_mfma_f32_16x16x32_bf16 v[118:121], v[118:121], v[78:81], v[126:129]
	s_add_i32 m0, s35, 0xc000
	s_nop 0
	buffer_load_dwordx4 v201, s[8:11], s36 offen lds
	ds_read_b128 v[126:129], v228 offset:0x2000
	s_waitcnt lgkmcnt(2)
	s_nop 0
	v_mfma_f32_16x16x32_bf16 v[110:113], v[138:141], v[50:53], v[110:113]
	v_mfma_f32_16x16x32_bf16 v[114:117], v[138:141], v[54:57], v[114:117]
	v_mfma_f32_16x16x32_bf16 v[102:105], v[138:141], v[58:61], v[102:105]
	v_mfma_f32_16x16x32_bf16 v[106:109], v[138:141], v[78:81], v[106:109]
	s_add_i32 m0, s35, 0x6000
	s_nop 0
	buffer_load_dwordx4 v201, s[64:67], s15 offen lds
	ds_read_b128 v[138:141], v228 offset:0x2800
	s_waitcnt lgkmcnt(2)
	s_nop 0
	v_mfma_f32_16x16x32_bf16 v[90:93], v[146:149], v[50:53], v[90:93]
	v_mfma_f32_16x16x32_bf16 v[94:97], v[146:149], v[54:57], v[94:97]
	v_mfma_f32_16x16x32_bf16 v[82:85], v[146:149], v[58:61], v[82:85]
	v_mfma_f32_16x16x32_bf16 v[86:89], v[146:149], v[78:81], v[86:89]
	s_add_i32 m0, s35, 0xe000
	s_nop 0
	buffer_load_dwordx4 v201, s[8:11], s15 offen lds
	ds_read_b128 v[146:149], v228 offset:0x3000
	s_waitcnt lgkmcnt(2)
	s_nop 0
	v_mfma_f32_16x16x32_bf16 v[70:73], v[126:129], v[50:53], v[70:73]
	v_mfma_f32_16x16x32_bf16 v[74:77], v[126:129], v[54:57], v[74:77]
	v_mfma_f32_16x16x32_bf16 v[62:65], v[126:129], v[58:61], v[62:65]
	v_mfma_f32_16x16x32_bf16 v[66:69], v[126:129], v[78:81], v[66:69]
	ds_read_b128 v[126:129], v228 offset:0x3800
	s_waitcnt lgkmcnt(2)
	v_xor_b32_e32 v166, 64, v229
	v_mfma_f32_16x16x32_bf16 v[42:45], v[138:141], v[50:53], v[42:45]
	v_mfma_f32_16x16x32_bf16 v[46:49], v[138:141], v[54:57], v[46:49]
	v_mfma_f32_16x16x32_bf16 v[34:37], v[138:141], v[58:61], v[34:37]
	v_mfma_f32_16x16x32_bf16 v[38:41], v[138:141], v[78:81], v[38:41]
	ds_read_b128 v[138:141], v166 offset:0
	ds_read_b128 v[158:161], v166 offset:0x800
	ds_read_b128 v[162:165], v166 offset:0x1000
	s_waitcnt lgkmcnt(4)
	s_nop 0
	v_mfma_f32_16x16x32_bf16 v[26:29], v[146:149], v[50:53], v[26:29]
	v_mfma_f32_16x16x32_bf16 v[30:33], v[146:149], v[54:57], v[30:33]
	v_mfma_f32_16x16x32_bf16 v[18:21], v[146:149], v[58:61], v[18:21]
	v_mfma_f32_16x16x32_bf16 v[22:25], v[146:149], v[78:81], v[22:25]
	ds_read_b128 v[166:169], v166 offset:0x1800
	ds_read_b128 v[146:149], v208 offset:0
	ds_read_b128 v[174:177], v208 offset:0x800
	s_waitcnt lgkmcnt(6)
	s_nop 0
	v_mfma_f32_16x16x32_bf16 v[10:13], v[126:129], v[50:53], v[10:13]
	v_mfma_f32_16x16x32_bf16 v[14:17], v[126:129], v[54:57], v[14:17]
	v_mfma_f32_16x16x32_bf16 v[2:5], v[126:129], v[58:61], v[2:5]
	v_mfma_f32_16x16x32_bf16 v[6:9], v[126:129], v[78:81], v[6:9]
	ds_read_b128 v[50:53], v208 offset:0x1000
	s_waitcnt lgkmcnt(2)
	s_nop 0
	v_mfma_f32_16x16x32_bf16 v[150:153], v[146:149], v[138:141], v[150:153]
	v_mfma_f32_16x16x32_bf16 v[154:157], v[146:149], v[158:161], v[154:157]
	v_mfma_f32_16x16x32_bf16 v[142:145], v[146:149], v[162:165], v[142:145]
	v_mfma_f32_16x16x32_bf16 v[146:149], v[146:149], v[166:169], v[98:101]
	ds_read_b128 v[54:57], v208 offset:0x1800
	s_waitcnt lgkmcnt(2)
	s_nop 0
	v_mfma_f32_16x16x32_bf16 v[130:133], v[174:177], v[138:141], v[130:133]
	v_mfma_f32_16x16x32_bf16 v[134:137], v[174:177], v[158:161], v[134:137]
	v_mfma_f32_16x16x32_bf16 v[122:125], v[174:177], v[162:165], v[122:125]
	v_mfma_f32_16x16x32_bf16 v[126:129], v[174:177], v[166:169], v[118:121]
	ds_read_b128 v[58:61], v208 offset:0x2000
	ds_read_b128 v[232:235], v208 offset:0x2800
	s_waitcnt lgkmcnt(3)
	s_nop 0
	v_mfma_f32_16x16x32_bf16 v[110:113], v[50:53], v[138:141], v[110:113]
	v_mfma_f32_16x16x32_bf16 v[114:117], v[50:53], v[158:161], v[114:117]
	v_mfma_f32_16x16x32_bf16 v[102:105], v[50:53], v[162:165], v[102:105]
	v_mfma_f32_16x16x32_bf16 v[106:109], v[50:53], v[166:169], v[106:109]
	ds_read_b128 v[236:239], v208 offset:0x3000
	s_waitcnt lgkmcnt(3)
	s_nop 0
	v_mfma_f32_16x16x32_bf16 v[90:93], v[54:57], v[138:141], v[90:93]
	v_mfma_f32_16x16x32_bf16 v[94:97], v[54:57], v[158:161], v[94:97]
	v_mfma_f32_16x16x32_bf16 v[82:85], v[54:57], v[162:165], v[82:85]
	v_mfma_f32_16x16x32_bf16 v[86:89], v[54:57], v[166:169], v[86:89]
	ds_read_b128 v[240:243], v208 offset:0x3800
	s_waitcnt lgkmcnt(3)
	s_nop 0
	v_mfma_f32_16x16x32_bf16 v[70:73], v[58:61], v[138:141], v[70:73]
	v_mfma_f32_16x16x32_bf16 v[74:77], v[58:61], v[158:161], v[74:77]
	v_mfma_f32_16x16x32_bf16 v[62:65], v[58:61], v[162:165], v[62:65]
	v_mfma_f32_16x16x32_bf16 v[66:69], v[58:61], v[166:169], v[66:69]
	s_setprio 0
	s_waitcnt lgkmcnt(0)
	s_waitcnt vmcnt(0)
	s_add_i32 s13, s13, 0x10000
	s_addk_i32 s15, 0x80
	s_cmp_eq_u32 s15, 0x60800
	s_mov_b32 s2, 0x10000
	s_barrier
	s_cbranch_scc0 .Lrot0_top_l
.Lrot0_top_n:
	v_add_u32_e32 v228, s2, v207
	v_add_u32_e32 v229, s2, v204
	ds_read_b128 v[50:53], v229 offset:0
	ds_read_b128 v[54:57], v229 offset:0x800
	ds_read_b128 v[58:61], v229 offset:0x1000
	ds_read_b128 v[78:81], v229 offset:0x1800
	ds_read_b128 v[98:101], v228 offset:0
	ds_read_b128 v[118:121], v228 offset:0x800
	s_setprio 1
	v_mfma_f32_16x16x32_bf16 v[42:45], v[232:235], v[138:141], v[42:45]
	v_mfma_f32_16x16x32_bf16 v[46:49], v[232:235], v[158:161], v[46:49]
	v_mfma_f32_16x16x32_bf16 v[34:37], v[232:235], v[162:165], v[34:37]
	v_mfma_f32_16x16x32_bf16 v[38:41], v[232:235], v[166:169], v[38:41]
	v_mfma_f32_16x16x32_bf16 v[26:29], v[236:239], v[138:141], v[26:29]
	v_mfma_f32_16x16x32_bf16 v[30:33], v[236:239], v[158:161], v[30:33]
	v_mfma_f32_16x16x32_bf16 v[18:21], v[236:239], v[162:165], v[18:21]
	v_mfma_f32_16x16x32_bf16 v[22:25], v[236:239], v[166:169], v[22:25]
	v_mfma_f32_16x16x32_bf16 v[10:13], v[240:243], v[138:141], v[10:13]
	v_mfma_f32_16x16x32_bf16 v[14:17], v[240:243], v[158:161], v[14:17]
	v_mfma_f32_16x16x32_bf16 v[2:5], v[240:243], v[162:165], v[2:5]
	v_mfma_f32_16x16x32_bf16 v[6:9], v[240:243], v[166:169], v[6:9]
	ds_read_b128 v[138:141], v228 offset:0x1000
	v_xor_b32_e32 v208, 64, v228
	s_waitcnt lgkmcnt(2)
	s_nop 0
	v_mfma_f32_16x16x32_bf16 v[150:153], v[98:101], v[50:53], v[150:153]
	v_mfma_f32_16x16x32_bf16 v[154:157], v[98:101], v[54:57], v[154:157]
	v_mfma_f32_16x16x32_bf16 v[142:145], v[98:101], v[58:61], v[142:145]
	v_mfma_f32_16x16x32_bf16 v[98:101], v[98:101], v[78:81], v[146:149]
	ds_read_b128 v[146:149], v228 offset:0x1800
	s_waitcnt lgkmcnt(2)
	s_nop 0
	v_mfma_f32_16x16x32_bf16 v[130:133], v[118:121], v[50:53], v[130:133]
	v_mfma_f32_16x16x32_bf16 v[134:137], v[118:121], v[54:57], v[134:137]
	v_mfma_f32_16x16x32_bf16 v[122:125], v[118:121], v[58:61], v[122:125]
	v_mfma_f32_16x16x32_bf16 v[118:121], v[118:121], v[78:81], v[126:129]
	ds_read_b128 v[126:129], v228 offset:0x2000
	s_waitcnt lgkmcnt(2)
	s_nop 0
	v_mfma_f32_16x16x32_bf16 v[110:113], v[138:141], v[50:53], v[110:113]
	v_mfma_f32_16x16x32_bf16 v[114:117], v[138:141], v[54:57], v[114:117]
	v_mfma_f32_16x16x32_bf16 v[102:105], v[138:141], v[58:61], v[102:105]
	v_mfma_f32_16x16x32_bf16 v[106:109], v[138:141], v[78:81], v[106:109]
	ds_read_b128 v[138:141], v228 offset:0x2800
	s_waitcnt lgkmcnt(2)
	s_nop 0
	v_mfma_f32_16x16x32_bf16 v[90:93], v[146:149], v[50:53], v[90:93]
	v_mfma_f32_16x16x32_bf16 v[94:97], v[146:149], v[54:57], v[94:97]
	v_mfma_f32_16x16x32_bf16 v[82:85], v[146:149], v[58:61], v[82:85]
	v_mfma_f32_16x16x32_bf16 v[86:89], v[146:149], v[78:81], v[86:89]
	ds_read_b128 v[146:149], v228 offset:0x3000
	s_waitcnt lgkmcnt(2)
	s_nop 0
	v_mfma_f32_16x16x32_bf16 v[70:73], v[126:129], v[50:53], v[70:73]
	v_mfma_f32_16x16x32_bf16 v[74:77], v[126:129], v[54:57], v[74:77]
	v_mfma_f32_16x16x32_bf16 v[62:65], v[126:129], v[58:61], v[62:65]
	v_mfma_f32_16x16x32_bf16 v[66:69], v[126:129], v[78:81], v[66:69]
	ds_read_b128 v[126:129], v228 offset:0x3800
	s_waitcnt lgkmcnt(2)
	v_xor_b32_e32 v166, 64, v229
	v_mfma_f32_16x16x32_bf16 v[42:45], v[138:141], v[50:53], v[42:45]
	v_mfma_f32_16x16x32_bf16 v[46:49], v[138:141], v[54:57], v[46:49]
	v_mfma_f32_16x16x32_bf16 v[34:37], v[138:141], v[58:61], v[34:37]
	v_mfma_f32_16x16x32_bf16 v[38:41], v[138:141], v[78:81], v[38:41]
	ds_read_b128 v[138:141], v166 offset:0
	ds_read_b128 v[158:161], v166 offset:0x800
	ds_read_b128 v[162:165], v166 offset:0x1000
	s_waitcnt lgkmcnt(4)
	s_nop 0
	v_mfma_f32_16x16x32_bf16 v[26:29], v[146:149], v[50:53], v[26:29]
	v_mfma_f32_16x16x32_bf16 v[30:33], v[146:149], v[54:57], v[30:33]
	v_mfma_f32_16x16x32_bf16 v[18:21], v[146:149], v[58:61], v[18:21]
	v_mfma_f32_16x16x32_bf16 v[22:25], v[146:149], v[78:81], v[22:25]
	ds_read_b128 v[166:169], v166 offset:0x1800
	ds_read_b128 v[146:149], v208 offset:0
	ds_read_b128 v[174:177], v208 offset:0x800
	s_waitcnt lgkmcnt(6)
	s_nop 0
	v_mfma_f32_16x16x32_bf16 v[10:13], v[126:129], v[50:53], v[10:13]
	v_mfma_f32_16x16x32_bf16 v[14:17], v[126:129], v[54:57], v[14:17]
	v_mfma_f32_16x16x32_bf16 v[2:5], v[126:129], v[58:61], v[2:5]
	v_mfma_f32_16x16x32_bf16 v[6:9], v[126:129], v[78:81], v[6:9]
	ds_read_b128 v[50:53], v208 offset:0x1000
	s_waitcnt lgkmcnt(2)
	s_nop 0
	v_mfma_f32_16x16x32_bf16 v[150:153], v[146:149], v[138:141], v[150:153]
	v_mfma_f32_16x16x32_bf16 v[154:157], v[146:149], v[158:161], v[154:157]
	v_mfma_f32_16x16x32_bf16 v[142:145], v[146:149], v[162:165], v[142:145]
	v_mfma_f32_16x16x32_bf16 v[146:149], v[146:149], v[166:169], v[98:101]
	ds_read_b128 v[54:57], v208 offset:0x1800
	s_waitcnt lgkmcnt(2)
	s_nop 0
	v_mfma_f32_16x16x32_bf16 v[130:133], v[174:177], v[138:141], v[130:133]
	v_mfma_f32_16x16x32_bf16 v[134:137], v[174:177], v[158:161], v[134:137]
	v_mfma_f32_16x16x32_bf16 v[122:125], v[174:177], v[162:165], v[122:125]
	v_mfma_f32_16x16x32_bf16 v[126:129], v[174:177], v[166:169], v[118:121]
	ds_read_b128 v[58:61], v208 offset:0x2000
	ds_read_b128 v[232:235], v208 offset:0x2800
	s_waitcnt lgkmcnt(3)
	s_nop 0
	v_mfma_f32_16x16x32_bf16 v[110:113], v[50:53], v[138:141], v[110:113]
	v_mfma_f32_16x16x32_bf16 v[114:117], v[50:53], v[158:161], v[114:117]
	v_mfma_f32_16x16x32_bf16 v[102:105], v[50:53], v[162:165], v[102:105]
	v_mfma_f32_16x16x32_bf16 v[106:109], v[50:53], v[166:169], v[106:109]
	ds_read_b128 v[236:239], v208 offset:0x3000
	s_waitcnt lgkmcnt(3)
	s_nop 0
	v_mfma_f32_16x16x32_bf16 v[90:93], v[54:57], v[138:141], v[90:93]
	v_mfma_f32_16x16x32_bf16 v[94:97], v[54:57], v[158:161], v[94:97]
	v_mfma_f32_16x16x32_bf16 v[82:85], v[54:57], v[162:165], v[82:85]
	v_mfma_f32_16x16x32_bf16 v[86:89], v[54:57], v[166:169], v[86:89]
	ds_read_b128 v[240:243], v208 offset:0x3800
	s_waitcnt lgkmcnt(3)
	s_nop 0
	v_mfma_f32_16x16x32_bf16 v[70:73], v[58:61], v[138:141], v[70:73]
	v_mfma_f32_16x16x32_bf16 v[74:77], v[58:61], v[158:161], v[74:77]
	v_mfma_f32_16x16x32_bf16 v[62:65], v[58:61], v[162:165], v[62:65]
	v_mfma_f32_16x16x32_bf16 v[66:69], v[58:61], v[166:169], v[66:69]
	s_setprio 0
	s_waitcnt lgkmcnt(0)
	s_add_i32 s13, s13, 0x10000
	s_addk_i32 s15, 0x80
	s_barrier
	v_mfma_f32_16x16x32_bf16 v[42:45], v[232:235], v[138:141], v[42:45]
	v_mfma_f32_16x16x32_bf16 v[46:49], v[232:235], v[158:161], v[46:49]
	v_mfma_f32_16x16x32_bf16 v[34:37], v[232:235], v[162:165], v[34:37]
	v_mfma_f32_16x16x32_bf16 v[38:41], v[232:235], v[166:169], v[38:41]
	v_mfma_f32_16x16x32_bf16 v[26:29], v[236:239], v[138:141], v[26:29]
	v_mfma_f32_16x16x32_bf16 v[30:33], v[236:239], v[158:161], v[30:33]
	v_mfma_f32_16x16x32_bf16 v[18:21], v[236:239], v[162:165], v[18:21]
	v_mfma_f32_16x16x32_bf16 v[22:25], v[236:239], v[166:169], v[22:25]
	v_mfma_f32_16x16x32_bf16 v[10:13], v[240:243], v[138:141], v[10:13]
	v_mfma_f32_16x16x32_bf16 v[14:17], v[240:243], v[158:161], v[14:17]
	v_mfma_f32_16x16x32_bf16 v[2:5], v[240:243], v[162:165], v[2:5]
	v_mfma_f32_16x16x32_bf16 v[6:9], v[240:243], v[166:169], v[6:9]
	s_nop 7
	s_nop 7
	s_nop 3

	.amdhsa_kernel _Z11mega_kernel6Paramsiii
		.amdhsa_group_segment_fixed_size 135184
		.amdhsa_private_segment_fixed_size 0
		.amdhsa_kernarg_size 488
		.amdhsa_user_sgpr_count 2
		.amdhsa_user_sgpr_dispatch_ptr 0
		.amdhsa_user_sgpr_queue_ptr 0
		.amdhsa_user_sgpr_kernarg_segment_ptr 1
		.amdhsa_user_sgpr_dispatch_id 0
		.amdhsa_user_sgpr_kernarg_preload_length 0
		.amdhsa_user_sgpr_kernarg_preload_offset 0
		.amdhsa_user_sgpr_private_segment_size 0
		.amdhsa_uses_dynamic_stack 0
		.amdhsa_enable_private_segment 0
		.amdhsa_system_sgpr_workgroup_id_x 1
		.amdhsa_system_sgpr_workgroup_id_y 0
		.amdhsa_system_sgpr_workgroup_id_z 0
		.amdhsa_system_sgpr_workgroup_info 0
		.amdhsa_system_vgpr_workitem_id 2
		.amdhsa_next_free_vgpr 248
		.amdhsa_next_free_sgpr 100
		.amdhsa_accum_offset 248
		.amdhsa_reserve_vcc 1
		.amdhsa_float_round_mode_32 0
		.amdhsa_float_round_mode_16_64 0
		.amdhsa_float_denorm_mode_32 3
		.amdhsa_float_denorm_mode_16_64 3
		.amdhsa_dx10_clamp 1
		.amdhsa_ieee_mode 1
		.amdhsa_fp16_overflow 0
		.amdhsa_tg_split 0
		.amdhsa_exception_fp_ieee_invalid_op 0
		.amdhsa_exception_fp_denorm_src 0
		.amdhsa_exception_fp_ieee_div_zero 0
		.amdhsa_exception_fp_ieee_overflow 0
		.amdhsa_exception_fp_ieee_underflow 0
		.amdhsa_exception_fp_ieee_inexact 0
		.amdhsa_exception_int_div_zero 0
	.end_amdhsa_kernel

.Lfunc_end0:
	.size	_Z11mega_kernel6Paramsiii, .Lfunc_end0-_Z11mega_kernel6Paramsiii
	.set _Z11mega_kernel6Paramsiii.num_vgpr, 248
	.set _Z11mega_kernel6Paramsiii.num_agpr, 0
	.set _Z11mega_kernel6Paramsiii.numbered_sgpr, 100
	.set _Z11mega_kernel6Paramsiii.num_named_barrier, 0
	.set _Z11mega_kernel6Paramsiii.private_seg_size, 0
	.set _Z11mega_kernel6Paramsiii.uses_vcc, 1
	.set _Z11mega_kernel6Paramsiii.uses_flat_scratch, 0
	.set _Z11mega_kernel6Paramsiii.has_dyn_sized_stack, 0
	.set _Z11mega_kernel6Paramsiii.has_recursion, 0
	.set _Z11mega_kernel6Paramsiii.has_indirect_call, 0

amdhsa.kernels:
  - .agpr_count:     0
    .args:
      - .offset:         0
        .size:           216
        .value_kind:     by_value
      - .offset:         216
        .size:           4
        .value_kind:     by_value
      - .offset:         220
        .size:           4
        .value_kind:     by_value
      - .offset:         224
        .size:           4
        .value_kind:     by_value
      - .offset:         232
        .size:           4
        .value_kind:     hidden_block_count_x
      - .offset:         236
        .size:           4
        .value_kind:     hidden_block_count_y
      - .offset:         240
        .size:           4
        .value_kind:     hidden_block_count_z
      - .offset:         244
        .size:           2
        .value_kind:     hidden_group_size_x
      - .offset:         246
        .size:           2
        .value_kind:     hidden_group_size_y
      - .offset:         248
        .size:           2
        .value_kind:     hidden_group_size_z
      - .offset:         250
        .size:           2
        .value_kind:     hidden_remainder_x
      - .offset:         252
        .size:           2
        .value_kind:     hidden_remainder_y
      - .offset:         254
        .size:           2
        .value_kind:     hidden_remainder_z
      - .offset:         272
        .size:           8
        .value_kind:     hidden_global_offset_x
      - .offset:         280
        .size:           8
        .value_kind:     hidden_global_offset_y
      - .offset:         288
        .size:           8
        .value_kind:     hidden_global_offset_z
      - .offset:         296
        .size:           2
        .value_kind:     hidden_grid_dims
      - .offset:         320
        .size:           8
        .value_kind:     hidden_multigrid_sync_arg
    .group_segment_fixed_size: 135184
    .kernarg_segment_align: 8
    .kernarg_segment_size: 488
    .language:       OpenCL C
    .language_version:
      - 2
      - 0
    .max_flat_workgroup_size: 512
    .name:           _Z11mega_kernel6Paramsiii
    .private_segment_fixed_size: 0
    .sgpr_count:     106
    .sgpr_spill_count: 70
    .symbol:         _Z11mega_kernel6Paramsiii.kd
    .uniform_work_group_size: 1
    .uses_dynamic_stack: false
    .vgpr_count:     248
    .vgpr_spill_count: 0
    .wavefront_size: 64
